# v15 + accumulator re-zeroing per GEMM unit with 63 v_mov_b64 instead of 127 v_mov_b32 (in-proj A/B, uq, ukv; the out-proj instance already had this form)
# speedup vs baseline: 1.0025x; 1.0020x over previous
.LBB0_267:
	s_ashr_i32 s43, s42, 31
	s_lshl_b64 s[12:13], s[42:43], 21
	s_add_u32 s48, s2, s12
	s_addc_u32 s49, s16, s13
	s_and_b64 s[12:13], s[46:47], exec
	s_cselect_b32 s21, s49, s9
	s_cselect_b32 s43, s48, s8
	s_ashr_i32 s45, s44, 31
	s_lshl_b64 s[12:13], s[44:45], 21
	s_add_u32 s50, s17, s12
	s_addc_u32 s51, s18, s13
	s_and_b64 s[12:13], s[46:47], exec
	s_cselect_b32 s45, s51, s11
	s_cselect_b32 s55, s50, s10
	s_lshl_b32 s3, s3, 8
	v_add_u32_e32 v4, s3, v171
	s_add_u32 s12, s8, 0x100080
	s_waitcnt lgkmcnt(0)
	v_ashrrev_i32_e32 v5, 31, v4
	s_addc_u32 s13, s9, 0
	v_lshl_add_u64 v[132:133], v[4:5], 2, s[6:7]
	s_add_u32 s58, s10, 0x100
	v_mov_b32_e32 v4, 0
	v_lshl_add_u64 v[134:135], s[12:13], 0, v[158:159]
	v_lshl_add_u64 v[136:137], s[12:13], 0, v[160:161]
	s_addc_u32 s59, s11, 0
	s_mov_b32 s60, -2
	s_mov_b64 s[10:11], 0
	v_mov_b32_e32 v5, v4
	v_mov_b64_e32 v[6:7], v[4:5]
	v_mov_b64_e32 v[8:9], v[4:5]
	v_mov_b64_e32 v[10:11], v[4:5]
	v_mov_b64_e32 v[12:13], v[4:5]
	v_mov_b64_e32 v[14:15], v[4:5]
	v_mov_b64_e32 v[16:17], v[4:5]
	v_mov_b64_e32 v[18:19], v[4:5]
	v_mov_b64_e32 v[20:21], v[4:5]
	v_mov_b64_e32 v[22:23], v[4:5]
	v_mov_b64_e32 v[24:25], v[4:5]
	v_mov_b64_e32 v[26:27], v[4:5]
	v_mov_b64_e32 v[28:29], v[4:5]
	v_mov_b64_e32 v[30:31], v[4:5]
	v_mov_b64_e32 v[32:33], v[4:5]
	v_mov_b64_e32 v[34:35], v[4:5]
	v_mov_b64_e32 v[36:37], v[4:5]
	v_mov_b64_e32 v[38:39], v[4:5]
	v_mov_b64_e32 v[40:41], v[4:5]
	v_mov_b64_e32 v[42:43], v[4:5]
	v_mov_b64_e32 v[44:45], v[4:5]
	v_mov_b64_e32 v[46:47], v[4:5]
	v_mov_b64_e32 v[48:49], v[4:5]
	v_mov_b64_e32 v[50:51], v[4:5]
	v_mov_b64_e32 v[52:53], v[4:5]
	v_mov_b64_e32 v[54:55], v[4:5]
	v_mov_b64_e32 v[56:57], v[4:5]
	v_mov_b64_e32 v[58:59], v[4:5]
	v_mov_b64_e32 v[60:61], v[4:5]
	v_mov_b64_e32 v[62:63], v[4:5]
	v_mov_b64_e32 v[64:65], v[4:5]
	v_mov_b64_e32 v[66:67], v[4:5]
	v_mov_b64_e32 v[68:69], v[4:5]
	v_mov_b64_e32 v[70:71], v[4:5]
	v_mov_b64_e32 v[72:73], v[4:5]
	v_mov_b64_e32 v[74:75], v[4:5]
	v_mov_b64_e32 v[76:77], v[4:5]
	v_mov_b64_e32 v[78:79], v[4:5]
	v_mov_b64_e32 v[80:81], v[4:5]
	v_mov_b64_e32 v[82:83], v[4:5]
	v_mov_b64_e32 v[84:85], v[4:5]
	v_mov_b64_e32 v[86:87], v[4:5]
	v_mov_b64_e32 v[88:89], v[4:5]
	v_mov_b64_e32 v[90:91], v[4:5]
	v_mov_b64_e32 v[92:93], v[4:5]
	v_mov_b64_e32 v[94:95], v[4:5]
	v_mov_b64_e32 v[96:97], v[4:5]
	v_mov_b64_e32 v[98:99], v[4:5]
	v_mov_b64_e32 v[100:101], v[4:5]
	v_mov_b64_e32 v[102:103], v[4:5]
	v_mov_b64_e32 v[104:105], v[4:5]
	v_mov_b64_e32 v[106:107], v[4:5]
	v_mov_b64_e32 v[108:109], v[4:5]
	v_mov_b64_e32 v[110:111], v[4:5]
	v_mov_b64_e32 v[112:113], v[4:5]
	v_mov_b64_e32 v[114:115], v[4:5]
	v_mov_b64_e32 v[116:117], v[4:5]
	v_mov_b64_e32 v[118:119], v[4:5]
	v_mov_b64_e32 v[120:121], v[4:5]
	v_mov_b64_e32 v[122:123], v[4:5]
	v_mov_b64_e32 v[124:125], v[4:5]
	v_mov_b64_e32 v[126:127], v[4:5]
	v_mov_b64_e32 v[128:129], v[4:5]
	v_mov_b64_e32 v[130:131], v[4:5]
	s_branch .LBB0_269

.LBB0_375:
	s_ashr_i32 s51, s50, 31
	s_lshl_b64 s[14:15], s[50:51], 21
	s_add_u32 s58, s2, s14
	s_addc_u32 s59, s16, s15
	s_and_b64 s[14:15], s[54:55], exec
	s_cselect_b32 s21, s59, s9
	s_cselect_b32 s51, s58, s8
	s_ashr_i32 s53, s52, 31
	s_lshl_b64 s[14:15], s[52:53], 21
	s_add_u32 s60, s17, s14
	s_addc_u32 s61, s18, s15
	s_and_b64 s[14:15], s[54:55], exec
	s_cselect_b32 s53, s61, s13
	s_cselect_b32 s67, s60, s12
	s_lshl_b32 s3, s10, 8
	s_waitcnt lgkmcnt(0)
	v_add_u32_e32 v4, s3, v169
	s_add_u32 s10, s8, 0x100080
	v_ashrrev_i32_e32 v5, 31, v4
	s_addc_u32 s11, s9, 0
	v_lshl_add_u64 v[132:133], v[4:5], 2, s[44:45]
	s_add_u32 s68, s12, 0x100
	v_mov_b32_e32 v4, 0
	v_lshl_add_u64 v[134:135], s[10:11], 0, v[158:159]
	v_lshl_add_u64 v[136:137], s[10:11], 0, v[160:161]
	s_addc_u32 s69, s13, 0
	s_mov_b32 s70, -2
	s_mov_b64 s[10:11], 0
	v_mov_b32_e32 v5, v4
	v_mov_b64_e32 v[6:7], v[4:5]
	v_mov_b64_e32 v[8:9], v[4:5]
	v_mov_b64_e32 v[10:11], v[4:5]
	v_mov_b64_e32 v[12:13], v[4:5]
	v_mov_b64_e32 v[14:15], v[4:5]
	v_mov_b64_e32 v[16:17], v[4:5]
	v_mov_b64_e32 v[18:19], v[4:5]
	v_mov_b64_e32 v[20:21], v[4:5]
	v_mov_b64_e32 v[22:23], v[4:5]
	v_mov_b64_e32 v[24:25], v[4:5]
	v_mov_b64_e32 v[26:27], v[4:5]
	v_mov_b64_e32 v[28:29], v[4:5]
	v_mov_b64_e32 v[30:31], v[4:5]
	v_mov_b64_e32 v[32:33], v[4:5]
	v_mov_b64_e32 v[34:35], v[4:5]
	v_mov_b64_e32 v[36:37], v[4:5]
	v_mov_b64_e32 v[38:39], v[4:5]
	v_mov_b64_e32 v[40:41], v[4:5]
	v_mov_b64_e32 v[42:43], v[4:5]
	v_mov_b64_e32 v[44:45], v[4:5]
	v_mov_b64_e32 v[46:47], v[4:5]
	v_mov_b64_e32 v[48:49], v[4:5]
	v_mov_b64_e32 v[50:51], v[4:5]
	v_mov_b64_e32 v[52:53], v[4:5]
	v_mov_b64_e32 v[54:55], v[4:5]
	v_mov_b64_e32 v[56:57], v[4:5]
	v_mov_b64_e32 v[58:59], v[4:5]
	v_mov_b64_e32 v[60:61], v[4:5]
	v_mov_b64_e32 v[62:63], v[4:5]
	v_mov_b64_e32 v[64:65], v[4:5]
	v_mov_b64_e32 v[66:67], v[4:5]
	v_mov_b64_e32 v[68:69], v[4:5]
	v_mov_b64_e32 v[70:71], v[4:5]
	v_mov_b64_e32 v[72:73], v[4:5]
	v_mov_b64_e32 v[74:75], v[4:5]
	v_mov_b64_e32 v[76:77], v[4:5]
	v_mov_b64_e32 v[78:79], v[4:5]
	v_mov_b64_e32 v[80:81], v[4:5]
	v_mov_b64_e32 v[82:83], v[4:5]
	v_mov_b64_e32 v[84:85], v[4:5]
	v_mov_b64_e32 v[86:87], v[4:5]
	v_mov_b64_e32 v[88:89], v[4:5]
	v_mov_b64_e32 v[90:91], v[4:5]
	v_mov_b64_e32 v[92:93], v[4:5]
	v_mov_b64_e32 v[94:95], v[4:5]
	v_mov_b64_e32 v[96:97], v[4:5]
	v_mov_b64_e32 v[98:99], v[4:5]
	v_mov_b64_e32 v[100:101], v[4:5]
	v_mov_b64_e32 v[102:103], v[4:5]
	v_mov_b64_e32 v[104:105], v[4:5]
	v_mov_b64_e32 v[106:107], v[4:5]
	v_mov_b64_e32 v[108:109], v[4:5]
	v_mov_b64_e32 v[110:111], v[4:5]
	v_mov_b64_e32 v[112:113], v[4:5]
	v_mov_b64_e32 v[114:115], v[4:5]
	v_mov_b64_e32 v[116:117], v[4:5]
	v_mov_b64_e32 v[118:119], v[4:5]
	v_mov_b64_e32 v[120:121], v[4:5]
	v_mov_b64_e32 v[122:123], v[4:5]
	v_mov_b64_e32 v[124:125], v[4:5]
	v_mov_b64_e32 v[126:127], v[4:5]
	v_mov_b64_e32 v[128:129], v[4:5]
	v_mov_b64_e32 v[130:131], v[4:5]
	s_branch .LBB0_377

.LBB0_437:
	s_ashr_i32 s47, s46, 31
	s_lshl_b64 s[0:1], s[46:47], 19
	s_add_u32 s48, s16, s0
	s_addc_u32 s49, s17, s1
	s_and_b64 s[0:1], s[36:37], exec
	s_cselect_b32 s3, s49, s9
	s_cselect_b32 s21, s48, s8
	s_ashr_i32 s45, s44, 31
	s_lshl_b64 s[0:1], s[44:45], 19
	s_add_u32 s50, s2, s0
	s_addc_u32 s51, s14, s1
	s_and_b64 s[0:1], s[36:37], exec
	s_cselect_b32 s47, s51, s11
	s_cselect_b32 s53, s50, s10
	s_lshl_b32 s45, s12, 8
	v_add_u32_e32 v4, s45, v189
	v_ashrrev_i32_e32 v5, 31, v4
	v_lshlrev_b64 v[6:7], 6, v[4:5]
	v_or_b32_e32 v4, 16, v4
	v_ashrrev_i32_e32 v5, 31, v4
	s_add_u32 s0, s8, 0x40080
	v_lshlrev_b64 v[4:5], 6, v[4:5]
	s_addc_u32 s1, s9, 0
	v_lshl_add_u64 v[162:163], s[40:41], 0, v[4:5]
	s_add_u32 s54, s10, 0x100
	v_mov_b32_e32 v4, 0
	v_lshl_add_u64 v[160:161], s[40:41], 0, v[6:7]
	v_lshl_add_u64 v[164:165], s[0:1], 0, v[156:157]
	v_lshl_add_u64 v[166:167], s[0:1], 0, v[158:159]
	s_addc_u32 s55, s11, 0
	s_mov_b32 s58, -2
	s_mov_b64 s[10:11], 0
	v_mov_b32_e32 v5, v4
	v_mov_b64_e32 v[6:7], v[4:5]
	v_mov_b64_e32 v[8:9], v[4:5]
	v_mov_b64_e32 v[10:11], v[4:5]
	v_mov_b64_e32 v[12:13], v[4:5]
	v_mov_b64_e32 v[14:15], v[4:5]
	v_mov_b64_e32 v[16:17], v[4:5]
	v_mov_b64_e32 v[18:19], v[4:5]
	v_mov_b64_e32 v[20:21], v[4:5]
	v_mov_b64_e32 v[22:23], v[4:5]
	v_mov_b64_e32 v[24:25], v[4:5]
	v_mov_b64_e32 v[26:27], v[4:5]
	v_mov_b64_e32 v[28:29], v[4:5]
	v_mov_b64_e32 v[30:31], v[4:5]
	v_mov_b64_e32 v[32:33], v[4:5]
	v_mov_b64_e32 v[34:35], v[4:5]
	v_mov_b64_e32 v[36:37], v[4:5]
	v_mov_b64_e32 v[38:39], v[4:5]
	v_mov_b64_e32 v[40:41], v[4:5]
	v_mov_b64_e32 v[42:43], v[4:5]
	v_mov_b64_e32 v[44:45], v[4:5]
	v_mov_b64_e32 v[46:47], v[4:5]
	v_mov_b64_e32 v[48:49], v[4:5]
	v_mov_b64_e32 v[50:51], v[4:5]
	v_mov_b64_e32 v[52:53], v[4:5]
	v_mov_b64_e32 v[54:55], v[4:5]
	v_mov_b64_e32 v[56:57], v[4:5]
	v_mov_b64_e32 v[58:59], v[4:5]
	v_mov_b64_e32 v[60:61], v[4:5]
	v_mov_b64_e32 v[62:63], v[4:5]
	v_mov_b64_e32 v[64:65], v[4:5]
	v_mov_b64_e32 v[66:67], v[4:5]
	v_mov_b64_e32 v[68:69], v[4:5]
	v_mov_b64_e32 v[70:71], v[4:5]
	v_mov_b64_e32 v[72:73], v[4:5]
	v_mov_b64_e32 v[74:75], v[4:5]
	v_mov_b64_e32 v[76:77], v[4:5]
	v_mov_b64_e32 v[78:79], v[4:5]
	v_mov_b64_e32 v[80:81], v[4:5]
	v_mov_b64_e32 v[82:83], v[4:5]
	v_mov_b64_e32 v[84:85], v[4:5]
	v_mov_b64_e32 v[86:87], v[4:5]
	v_mov_b64_e32 v[88:89], v[4:5]
	v_mov_b64_e32 v[90:91], v[4:5]
	v_mov_b64_e32 v[92:93], v[4:5]
	v_mov_b64_e32 v[94:95], v[4:5]
	v_mov_b64_e32 v[96:97], v[4:5]
	v_mov_b64_e32 v[98:99], v[4:5]
	v_mov_b64_e32 v[100:101], v[4:5]
	v_mov_b64_e32 v[102:103], v[4:5]
	v_mov_b64_e32 v[104:105], v[4:5]
	v_mov_b64_e32 v[106:107], v[4:5]
	v_mov_b64_e32 v[108:109], v[4:5]
	v_mov_b64_e32 v[110:111], v[4:5]
	v_mov_b64_e32 v[112:113], v[4:5]
	v_mov_b64_e32 v[114:115], v[4:5]
	v_mov_b64_e32 v[116:117], v[4:5]
	v_mov_b64_e32 v[118:119], v[4:5]
	v_mov_b64_e32 v[120:121], v[4:5]
	v_mov_b64_e32 v[122:123], v[4:5]
	v_mov_b64_e32 v[124:125], v[4:5]
	v_mov_b64_e32 v[126:127], v[4:5]
	v_mov_b64_e32 v[128:129], v[4:5]
	v_mov_b64_e32 v[130:131], v[4:5]
	s_branch .LBB0_439

.LBB0_465:
	s_ashr_i32 s15, s14, 31
	s_lshl_b64 s[18:19], s[14:15], 18
	s_add_u32 s36, s23, s18
	s_addc_u32 s37, s24, s19
	s_and_b64 s[18:19], s[16:17], exec
	s_cselect_b32 s15, s37, s43
	s_cselect_b32 s18, s36, s42
	s_ashr_i32 s13, s12, 31
	s_lshl_b64 s[40:41], s[12:13], 18
	s_add_u32 s40, s2, s40
	s_addc_u32 s41, s3, s41
	s_and_b64 s[46:47], s[16:17], exec
	s_cselect_b32 s19, s41, s1
	s_cselect_b32 s52, s40, s0
	s_lshl_b32 s13, s44, 8
	v_add_u32_e32 v4, s13, v154
	v_ashrrev_i32_e32 v5, 31, v4
	v_lshlrev_b64 v[6:7], 5, v[4:5]
	v_or_b32_e32 v4, 16, v4
	v_ashrrev_i32_e32 v5, 31, v4
	s_add_u32 s44, s42, 0x20080
	v_lshlrev_b64 v[4:5], 5, v[4:5]
	s_addc_u32 s45, s43, 0
	v_lshl_add_u64 v[146:147], s[8:9], 0, v[4:5]
	s_add_u32 s53, s0, 0x100
	v_mov_b32_e32 v4, 0
	v_lshl_add_u64 v[144:145], s[8:9], 0, v[6:7]
	v_lshl_add_u64 v[148:149], s[44:45], 0, v[140:141]
	v_lshl_add_u64 v[150:151], s[44:45], 0, v[142:143]
	s_addc_u32 s54, s1, 0
	s_mov_b32 s55, -2
	s_mov_b64 s[44:45], 0
	v_mov_b32_e32 v5, v4
	v_mov_b64_e32 v[6:7], v[4:5]
	v_mov_b64_e32 v[8:9], v[4:5]
	v_mov_b64_e32 v[10:11], v[4:5]
	v_mov_b64_e32 v[12:13], v[4:5]
	v_mov_b64_e32 v[14:15], v[4:5]
	v_mov_b64_e32 v[16:17], v[4:5]
	v_mov_b64_e32 v[18:19], v[4:5]
	v_mov_b64_e32 v[20:21], v[4:5]
	v_mov_b64_e32 v[22:23], v[4:5]
	v_mov_b64_e32 v[24:25], v[4:5]
	v_mov_b64_e32 v[26:27], v[4:5]
	v_mov_b64_e32 v[28:29], v[4:5]
	v_mov_b64_e32 v[30:31], v[4:5]
	v_mov_b64_e32 v[32:33], v[4:5]
	v_mov_b64_e32 v[34:35], v[4:5]
	v_mov_b64_e32 v[36:37], v[4:5]
	v_mov_b64_e32 v[38:39], v[4:5]
	v_mov_b64_e32 v[40:41], v[4:5]
	v_mov_b64_e32 v[42:43], v[4:5]
	v_mov_b64_e32 v[44:45], v[4:5]
	v_mov_b64_e32 v[46:47], v[4:5]
	v_mov_b64_e32 v[48:49], v[4:5]
	v_mov_b64_e32 v[50:51], v[4:5]
	v_mov_b64_e32 v[52:53], v[4:5]
	v_mov_b64_e32 v[54:55], v[4:5]
	v_mov_b64_e32 v[56:57], v[4:5]
	v_mov_b64_e32 v[58:59], v[4:5]
	v_mov_b64_e32 v[60:61], v[4:5]
	v_mov_b64_e32 v[62:63], v[4:5]
	v_mov_b64_e32 v[64:65], v[4:5]
	v_mov_b64_e32 v[66:67], v[4:5]
	v_mov_b64_e32 v[68:69], v[4:5]
	v_mov_b64_e32 v[70:71], v[4:5]
	v_mov_b64_e32 v[72:73], v[4:5]
	v_mov_b64_e32 v[74:75], v[4:5]
	v_mov_b64_e32 v[76:77], v[4:5]
	v_mov_b64_e32 v[78:79], v[4:5]
	v_mov_b64_e32 v[80:81], v[4:5]
	v_mov_b64_e32 v[82:83], v[4:5]
	v_mov_b64_e32 v[84:85], v[4:5]
	v_mov_b64_e32 v[86:87], v[4:5]
	v_mov_b64_e32 v[88:89], v[4:5]
	v_mov_b64_e32 v[90:91], v[4:5]
	v_mov_b64_e32 v[92:93], v[4:5]
	v_mov_b64_e32 v[94:95], v[4:5]
	v_mov_b64_e32 v[96:97], v[4:5]
	v_mov_b64_e32 v[98:99], v[4:5]
	v_mov_b64_e32 v[100:101], v[4:5]
	v_mov_b64_e32 v[102:103], v[4:5]
	v_mov_b64_e32 v[104:105], v[4:5]
	v_mov_b64_e32 v[106:107], v[4:5]
	v_mov_b64_e32 v[108:109], v[4:5]
	v_mov_b64_e32 v[110:111], v[4:5]
	v_mov_b64_e32 v[112:113], v[4:5]
	v_mov_b64_e32 v[114:115], v[4:5]
	v_mov_b64_e32 v[116:117], v[4:5]
	v_mov_b64_e32 v[118:119], v[4:5]
	v_mov_b64_e32 v[120:121], v[4:5]
	v_mov_b64_e32 v[122:123], v[4:5]
	v_mov_b64_e32 v[124:125], v[4:5]
	v_mov_b64_e32 v[126:127], v[4:5]
	v_mov_b64_e32 v[128:129], v[4:5]
	v_mov_b64_e32 v[130:131], v[4:5]
	s_branch .LBB0_467
